# combined: shift/mask tile order, SADDR LDS-DMA in G1 K loop, first K iteration peeled with srcC=0 in G1 and G2 (no accumulator zeroing)
# speedup vs baseline: 1.0075x; 1.0075x over previous
.LBB0_56:
	s_ashr_i32 s95, s94, 31
	s_lshl_b64 s[6:7], s[94:95], 19
	v_readlane_b32 s9, v253, 5
	s_add_u32 s80, s9, s6
	v_readlane_b32 s6, v253, 6
	s_addc_u32 s81, s6, s7
	s_and_b64 s[6:7], s[42:43], exec
	s_cselect_b32 s9, s81, s1
	s_cselect_b32 s11, s80, s0
	s_ashr_i32 s93, s92, 31
	s_lshl_b64 s[6:7], s[92:93], 19
	v_readlane_b32 s12, v253, 61
	s_add_u32 s82, s12, s6
	v_readlane_b32 s6, v253, 62
	s_addc_u32 s83, s6, s7
	s_and_b64 s[6:7], s[42:43], exec
	s_cselect_b32 s12, s83, s5
	s_cselect_b32 s13, s82, s4
	s_add_u32 s0, s0, 0x40080
	s_addc_u32 s1, s1, 0
	s_add_u32 s14, s4, 0x100
	s_addc_u32 s15, s5, 0
	s_mov_b32 s16, -2
	s_add_u32 s4, s0, 0xfffc0080
	s_addc_u32 s5, s1, -1
	s_add_i32 s17, 0, 0x10000
	s_cmp_eq_u32 s16, 12
	s_cselect_b32 s7, s9, s5
	s_cselect_b32 s6, s11, s4
	v_add_u32_e32 v0, s17, v198
	s_cselect_b32 s5, s12, s15
	s_cselect_b32 s4, s13, s14
	s_add_i32 s20, 0, 0x14000
	ds_read_b128 v[18:21], v0
	ds_read_b128 v[22:25], v0 offset:1024
	ds_read_b128 v[34:37], v0 offset:2048
	ds_read_b128 v[38:41], v0 offset:3072
	v_add_u32_e32 v0, s20, v198
	ds_read_b128 v[146:149], v0
	ds_read_b128 v[150:153], v0 offset:1024
	ds_read_b128 v[172:175], v0 offset:2048
	ds_read_b128 v[176:179], v0 offset:3072
	s_add_i32 m0, s69, 0xc000
	ds_read_b128 v[180:183], v200
	ds_read_b128 v[184:187], v200 offset:1024
	ds_read_b128 v[202:205], v200 offset:2048
	ds_read_b128 v[206:209], v200 offset:3072
	ds_read_b128 v[210:213], v200 offset:4096
	ds_read_b128 v[214:217], v200 offset:5120
	ds_read_b128 v[218:221], v200 offset:6144
	ds_read_b128 v[234:237], v200 offset:7168
	global_load_lds_dwordx4 v168, s[0:1]
	s_add_i32 m0, s69, 0xe000
	s_nop 0
	global_load_lds_dwordx4 v170, s[0:1]
	s_waitcnt vmcnt(8)
	s_waitcnt lgkmcnt(0)
	s_barrier
	s_setprio 1
	s_waitcnt lgkmcnt(0)
	v_mfma_f32_16x16x32_bf16 v[142:145], v[18:21], v[180:183], 0
	v_mfma_f32_16x16x32_bf16 v[138:141], v[34:37], v[180:183], 0
	v_mfma_f32_16x16x32_bf16 v[126:129], v[18:21], v[202:205], 0
	v_mfma_f32_16x16x32_bf16 v[122:125], v[34:37], v[202:205], 0
	v_mfma_f32_16x16x32_bf16 v[110:113], v[18:21], v[210:213], 0
	v_mfma_f32_16x16x32_bf16 v[106:109], v[34:37], v[210:213], 0
	v_mfma_f32_16x16x32_bf16 v[94:97], v[18:21], v[218:221], 0
	v_mfma_f32_16x16x32_bf16 v[90:93], v[34:37], v[218:221], 0
	v_mfma_f32_16x16x32_bf16 v[142:145], v[22:25], v[184:187], v[142:145]
	v_mfma_f32_16x16x32_bf16 v[138:141], v[38:41], v[184:187], v[138:141]
	v_mfma_f32_16x16x32_bf16 v[126:129], v[22:25], v[206:209], v[126:129]
	v_mfma_f32_16x16x32_bf16 v[122:125], v[38:41], v[206:209], v[122:125]
	v_mfma_f32_16x16x32_bf16 v[110:113], v[22:25], v[214:217], v[110:113]
	v_mfma_f32_16x16x32_bf16 v[106:109], v[38:41], v[214:217], v[106:109]
	v_mfma_f32_16x16x32_bf16 v[94:97], v[22:25], v[234:237], v[94:97]
	v_mfma_f32_16x16x32_bf16 v[90:93], v[38:41], v[234:237], v[90:93]
	s_setprio 0
	s_setprio 1
	v_mfma_f32_16x16x32_bf16 v[134:137], v[146:149], v[180:183], 0
	v_mfma_f32_16x16x32_bf16 v[130:133], v[172:175], v[180:183], 0
	v_mfma_f32_16x16x32_bf16 v[118:121], v[146:149], v[202:205], 0
	v_mfma_f32_16x16x32_bf16 v[114:117], v[172:175], v[202:205], 0
	v_mfma_f32_16x16x32_bf16 v[102:105], v[146:149], v[210:213], 0
	v_mfma_f32_16x16x32_bf16 v[98:101], v[172:175], v[210:213], 0
	v_mfma_f32_16x16x32_bf16 v[86:89], v[146:149], v[218:221], 0
	v_mfma_f32_16x16x32_bf16 v[82:85], v[172:175], v[218:221], 0
	v_mfma_f32_16x16x32_bf16 v[134:137], v[150:153], v[184:187], v[134:137]
	v_mfma_f32_16x16x32_bf16 v[130:133], v[176:179], v[184:187], v[130:133]
	v_mfma_f32_16x16x32_bf16 v[118:121], v[150:153], v[206:209], v[118:121]
	v_mfma_f32_16x16x32_bf16 v[114:117], v[176:179], v[206:209], v[114:117]
	v_mfma_f32_16x16x32_bf16 v[102:105], v[150:153], v[214:217], v[102:105]
	v_mfma_f32_16x16x32_bf16 v[98:101], v[176:179], v[214:217], v[98:101]
	v_mfma_f32_16x16x32_bf16 v[86:89], v[150:153], v[234:237], v[86:89]
	v_mfma_f32_16x16x32_bf16 v[82:85], v[176:179], v[234:237], v[82:85]
	s_setprio 0
	s_barrier
	s_add_i32 s17, s17, s87
	s_mov_b32 m0, s17
	ds_read_b128 v[180:183], v200 offset:16384
	ds_read_b128 v[184:187], v200 offset:17408
	ds_read_b128 v[202:205], v200 offset:18432
	ds_read_b128 v[206:209], v200 offset:19456
	ds_read_b128 v[210:213], v200 offset:20480
	ds_read_b128 v[214:217], v200 offset:21504
	ds_read_b128 v[218:221], v200 offset:22528
	ds_read_b128 v[234:237], v200 offset:23552
	global_load_lds_dwordx4 v158, s[4:5]
	s_add_i32 m0, s17, 0x2000
	s_add_u32 s98, s6, s48
	s_addc_u32 s99, s7, s49
	s_add_u32 s18, s4, 0x40000
	s_addc_u32 s19, s5, 0
	s_add_i32 s17, s20, s87
	global_load_lds_dwordx4 v154, s[4:5]
	s_mov_b32 m0, s17
	s_nop 0
	global_load_lds_dwordx4 v158, s[18:19]
	s_add_i32 m0, s17, 0x2000
	s_nop 0
	global_load_lds_dwordx4 v154, s[18:19]
	s_mov_b32 m0, s69
	s_nop 0
	global_load_lds_dwordx4 v160, s[6:7]
	s_mov_b32 m0, s76
	s_nop 0
	global_load_lds_dwordx4 v156, s[6:7]
	s_waitcnt vmcnt(8)
	s_waitcnt lgkmcnt(0)
	s_barrier
	s_setprio 1
	s_waitcnt lgkmcnt(0)
	v_mfma_f32_16x16x32_bf16 v[78:81], v[18:21], v[180:183], 0
	v_mfma_f32_16x16x32_bf16 v[74:77], v[34:37], v[180:183], 0
	v_mfma_f32_16x16x32_bf16 v[62:65], v[18:21], v[202:205], 0
	v_mfma_f32_16x16x32_bf16 v[58:61], v[34:37], v[202:205], 0
	v_mfma_f32_16x16x32_bf16 v[46:49], v[18:21], v[210:213], 0
	v_mfma_f32_16x16x32_bf16 v[42:45], v[34:37], v[210:213], 0
	v_mfma_f32_16x16x32_bf16 v[14:17], v[18:21], v[218:221], 0
	v_mfma_f32_16x16x32_bf16 v[10:13], v[34:37], v[218:221], 0
	v_mfma_f32_16x16x32_bf16 v[78:81], v[22:25], v[184:187], v[78:81]
	v_mfma_f32_16x16x32_bf16 v[74:77], v[38:41], v[184:187], v[74:77]
	v_mfma_f32_16x16x32_bf16 v[62:65], v[22:25], v[206:209], v[62:65]
	v_mfma_f32_16x16x32_bf16 v[58:61], v[38:41], v[206:209], v[58:61]
	v_mfma_f32_16x16x32_bf16 v[46:49], v[22:25], v[214:217], v[46:49]
	v_mfma_f32_16x16x32_bf16 v[42:45], v[38:41], v[214:217], v[42:45]
	v_mfma_f32_16x16x32_bf16 v[14:17], v[22:25], v[234:237], v[14:17]
	v_mfma_f32_16x16x32_bf16 v[10:13], v[38:41], v[234:237], v[10:13]
	s_setprio 0
	s_setprio 1
	v_mfma_f32_16x16x32_bf16 v[30:33], v[146:149], v[210:213], 0
	v_mfma_f32_16x16x32_bf16 v[26:29], v[172:175], v[210:213], 0
	v_mfma_f32_16x16x32_bf16 v[6:9], v[146:149], v[218:221], 0
	v_mfma_f32_16x16x32_bf16 v[2:5], v[172:175], v[218:221], 0
	v_mfma_f32_16x16x32_bf16 v[18:21], v[146:149], v[180:183], 0
	v_mfma_f32_16x16x32_bf16 v[22:25], v[172:175], v[180:183], 0
	v_mfma_f32_16x16x32_bf16 v[34:37], v[146:149], v[202:205], 0
	v_mfma_f32_16x16x32_bf16 v[38:41], v[172:175], v[202:205], 0
	v_mfma_f32_16x16x32_bf16 v[30:33], v[150:153], v[214:217], v[30:33]
	v_mfma_f32_16x16x32_bf16 v[26:29], v[176:179], v[214:217], v[26:29]
	v_mfma_f32_16x16x32_bf16 v[6:9], v[150:153], v[234:237], v[6:9]
	v_mfma_f32_16x16x32_bf16 v[2:5], v[176:179], v[234:237], v[2:5]
	v_mfma_f32_16x16x32_bf16 v[18:21], v[150:153], v[184:187], v[18:21]
	v_mfma_f32_16x16x32_bf16 v[22:25], v[176:179], v[184:187], v[22:25]
	v_mfma_f32_16x16x32_bf16 v[34:37], v[150:153], v[206:209], v[34:37]
	v_mfma_f32_16x16x32_bf16 v[38:41], v[176:179], v[206:209], v[38:41]
	s_setprio 0
	s_barrier
	s_add_i32 s17, 0, 0x18000
	v_add_u32_e32 v0, s17, v198
	s_add_i32 s18, 0, 0x1c000
	ds_read_b128 v[50:53], v0
	ds_read_b128 v[54:57], v0 offset:1024
	ds_read_b128 v[66:69], v0 offset:2048
	ds_read_b128 v[70:73], v0 offset:3072
	v_add_u32_e32 v0, s18, v198
	ds_read_b128 v[146:149], v0
	ds_read_b128 v[150:153], v0 offset:1024
	ds_read_b128 v[172:175], v0 offset:2048
	ds_read_b128 v[176:179], v0 offset:3072
	s_add_u32 s6, s6, 0x40000
	s_addc_u32 s7, s7, 0
	s_mov_b32 m0, s77
	ds_read_b128 v[180:183], v200 offset:32768
	ds_read_b128 v[184:187], v200 offset:33792
	ds_read_b128 v[202:205], v200 offset:34816
	ds_read_b128 v[206:209], v200 offset:35840
	ds_read_b128 v[210:213], v200 offset:36864
	ds_read_b128 v[214:217], v200 offset:37888
	ds_read_b128 v[218:221], v200 offset:38912
	ds_read_b128 v[234:237], v200 offset:39936
	global_load_lds_dwordx4 v160, s[6:7]
	s_mov_b32 m0, s96
	s_nop 0
	global_load_lds_dwordx4 v156, s[6:7]
	s_waitcnt vmcnt(8)
	s_waitcnt lgkmcnt(0)
	s_barrier
	s_setprio 1
	s_waitcnt lgkmcnt(0)
	v_mfma_f32_16x16x32_bf16 v[142:145], v[50:53], v[180:183], v[142:145]
	v_mfma_f32_16x16x32_bf16 v[138:141], v[66:69], v[180:183], v[138:141]
	v_mfma_f32_16x16x32_bf16 v[126:129], v[50:53], v[202:205], v[126:129]
	v_mfma_f32_16x16x32_bf16 v[122:125], v[66:69], v[202:205], v[122:125]
	v_mfma_f32_16x16x32_bf16 v[110:113], v[50:53], v[210:213], v[110:113]
	v_mfma_f32_16x16x32_bf16 v[106:109], v[66:69], v[210:213], v[106:109]
	v_mfma_f32_16x16x32_bf16 v[94:97], v[50:53], v[218:221], v[94:97]
	v_mfma_f32_16x16x32_bf16 v[90:93], v[66:69], v[218:221], v[90:93]
	v_mfma_f32_16x16x32_bf16 v[142:145], v[54:57], v[184:187], v[142:145]
	v_mfma_f32_16x16x32_bf16 v[138:141], v[70:73], v[184:187], v[138:141]
	v_mfma_f32_16x16x32_bf16 v[126:129], v[54:57], v[206:209], v[126:129]
	v_mfma_f32_16x16x32_bf16 v[122:125], v[70:73], v[206:209], v[122:125]
	v_mfma_f32_16x16x32_bf16 v[110:113], v[54:57], v[214:217], v[110:113]
	v_mfma_f32_16x16x32_bf16 v[106:109], v[70:73], v[214:217], v[106:109]
	v_mfma_f32_16x16x32_bf16 v[94:97], v[54:57], v[234:237], v[94:97]
	v_mfma_f32_16x16x32_bf16 v[90:93], v[70:73], v[234:237], v[90:93]
	s_setprio 0
	s_setprio 1
	v_mfma_f32_16x16x32_bf16 v[134:137], v[146:149], v[180:183], v[134:137]
	v_mfma_f32_16x16x32_bf16 v[130:133], v[172:175], v[180:183], v[130:133]
	v_mfma_f32_16x16x32_bf16 v[118:121], v[146:149], v[202:205], v[118:121]
	v_mfma_f32_16x16x32_bf16 v[114:117], v[172:175], v[202:205], v[114:117]
	v_mfma_f32_16x16x32_bf16 v[102:105], v[146:149], v[210:213], v[102:105]
	v_mfma_f32_16x16x32_bf16 v[98:101], v[172:175], v[210:213], v[98:101]
	v_mfma_f32_16x16x32_bf16 v[86:89], v[146:149], v[218:221], v[86:89]
	v_mfma_f32_16x16x32_bf16 v[82:85], v[172:175], v[218:221], v[82:85]
	v_mfma_f32_16x16x32_bf16 v[134:137], v[150:153], v[184:187], v[134:137]
	v_mfma_f32_16x16x32_bf16 v[130:133], v[176:179], v[184:187], v[130:133]
	v_mfma_f32_16x16x32_bf16 v[118:121], v[150:153], v[206:209], v[118:121]
	v_mfma_f32_16x16x32_bf16 v[114:117], v[176:179], v[206:209], v[114:117]
	v_mfma_f32_16x16x32_bf16 v[102:105], v[150:153], v[214:217], v[102:105]
	v_mfma_f32_16x16x32_bf16 v[98:101], v[176:179], v[214:217], v[98:101]
	v_mfma_f32_16x16x32_bf16 v[86:89], v[150:153], v[234:237], v[86:89]
	v_mfma_f32_16x16x32_bf16 v[82:85], v[176:179], v[234:237], v[82:85]
	s_setprio 0
	s_barrier
	s_add_i32 s6, s17, s87
	s_add_u32 vcc_lo, s4, s48
	s_addc_u32 vcc_hi, s5, s49
	s_mov_b32 m0, s6
	ds_read_b128 v[180:183], v200 offset:49152
	ds_read_b128 v[184:187], v200 offset:50176
	ds_read_b128 v[202:205], v200 offset:51200
	ds_read_b128 v[206:209], v200 offset:52224
	ds_read_b128 v[210:213], v200 offset:53248
	ds_read_b128 v[214:217], v200 offset:54272
	ds_read_b128 v[218:221], v200 offset:55296
	ds_read_b128 v[234:237], v200 offset:56320
	global_load_lds_dwordx4 v158, vcc
	s_add_i32 m0, s6, 0x2000
	s_add_u32 s4, s4, 0x40080
	s_addc_u32 s5, s5, 0
	s_add_i32 s6, s18, s87
	global_load_lds_dwordx4 v154, vcc
	s_mov_b32 m0, s6
	s_nop 0
	global_load_lds_dwordx4 v158, s[4:5]
	s_add_i32 m0, s6, 0x2000
	s_nop 0
	global_load_lds_dwordx4 v154, s[4:5]
	s_mov_b32 m0, s74
	s_nop 0
	global_load_lds_dwordx4 v160, s[98:99]
	s_mov_b32 m0, s75
	s_nop 0
	global_load_lds_dwordx4 v156, s[98:99]
	s_waitcnt vmcnt(8)
	s_waitcnt lgkmcnt(0)
	s_barrier
	s_setprio 1
	s_waitcnt lgkmcnt(0)
	v_mfma_f32_16x16x32_bf16 v[78:81], v[50:53], v[180:183], v[78:81]
	v_mfma_f32_16x16x32_bf16 v[74:77], v[66:69], v[180:183], v[74:77]
	v_mfma_f32_16x16x32_bf16 v[62:65], v[50:53], v[202:205], v[62:65]
	v_mfma_f32_16x16x32_bf16 v[58:61], v[66:69], v[202:205], v[58:61]
	v_mfma_f32_16x16x32_bf16 v[46:49], v[50:53], v[210:213], v[46:49]
	v_mfma_f32_16x16x32_bf16 v[42:45], v[66:69], v[210:213], v[42:45]
	v_mfma_f32_16x16x32_bf16 v[14:17], v[50:53], v[218:221], v[14:17]
	v_mfma_f32_16x16x32_bf16 v[10:13], v[66:69], v[218:221], v[10:13]
	v_mfma_f32_16x16x32_bf16 v[78:81], v[54:57], v[184:187], v[78:81]
	v_mfma_f32_16x16x32_bf16 v[74:77], v[70:73], v[184:187], v[74:77]
	v_mfma_f32_16x16x32_bf16 v[62:65], v[54:57], v[206:209], v[62:65]
	v_mfma_f32_16x16x32_bf16 v[58:61], v[70:73], v[206:209], v[58:61]
	v_mfma_f32_16x16x32_bf16 v[46:49], v[54:57], v[214:217], v[46:49]
	v_mfma_f32_16x16x32_bf16 v[42:45], v[70:73], v[214:217], v[42:45]
	v_mfma_f32_16x16x32_bf16 v[14:17], v[54:57], v[234:237], v[14:17]
	v_mfma_f32_16x16x32_bf16 v[10:13], v[70:73], v[234:237], v[10:13]
	s_setprio 0
	s_setprio 1
	v_mfma_f32_16x16x32_bf16 v[18:21], v[146:149], v[180:183], v[18:21]
	v_mfma_f32_16x16x32_bf16 v[70:73], v[150:153], v[184:187], v[18:21]
	v_mfma_f32_16x16x32_bf16 v[18:21], v[172:175], v[180:183], v[22:25]
	v_mfma_f32_16x16x32_bf16 v[66:69], v[176:179], v[184:187], v[18:21]
	v_mfma_f32_16x16x32_bf16 v[18:21], v[146:149], v[202:205], v[34:37]
	v_mfma_f32_16x16x32_bf16 v[54:57], v[150:153], v[206:209], v[18:21]
	v_mfma_f32_16x16x32_bf16 v[18:21], v[172:175], v[202:205], v[38:41]
	v_mfma_f32_16x16x32_bf16 v[50:53], v[176:179], v[206:209], v[18:21]
	v_mfma_f32_16x16x32_bf16 v[18:21], v[146:149], v[210:213], v[30:33]
	v_mfma_f32_16x16x32_bf16 v[30:33], v[150:153], v[214:217], v[18:21]
	v_mfma_f32_16x16x32_bf16 v[18:21], v[172:175], v[210:213], v[26:29]
	v_mfma_f32_16x16x32_bf16 v[6:9], v[146:149], v[218:221], v[6:9]
	v_mfma_f32_16x16x32_bf16 v[2:5], v[172:175], v[218:221], v[2:5]
	v_mfma_f32_16x16x32_bf16 v[26:29], v[176:179], v[214:217], v[18:21]
	v_mfma_f32_16x16x32_bf16 v[6:9], v[150:153], v[234:237], v[6:9]
	v_mfma_f32_16x16x32_bf16 v[2:5], v[176:179], v[234:237], v[2:5]
	s_setprio 0
	s_barrier
	s_add_i32 s16, s16, 2
	s_add_u32 s0, s0, 0x100
	s_addc_u32 s1, s1, 0
	s_add_u32 s14, s14, 0x100
	s_addc_u32 s15, s15, 0
	s_cmp_gt_u32 s16, 13
	s_cbranch_scc0 .LBB0_57

.LBB0_1369:
	s_ashr_i32 s9, s8, 31
	s_lshl_b64 s[10:11], s[8:9], 19
	v_readlane_b32 s7, v253, 15
	s_add_u32 s10, s7, s10
	v_readlane_b32 s7, v253, 16
	s_addc_u32 s11, s7, s11
	s_and_b64 s[12:13], s[38:39], exec
	s_cselect_b32 s9, s11, s15
	s_cselect_b32 s69, s10, s14
	s_ashr_i32 s7, s6, 31
	s_lshl_b64 s[12:13], s[6:7], 19
	s_add_u32 s12, s40, s12
	s_addc_u32 s13, s41, s13
	s_and_b64 s[18:19], s[38:39], exec
	s_cselect_b32 s7, s13, s17
	s_cselect_b32 s70, s12, s16
	s_add_u32 s14, s14, 0x40080
	s_addc_u32 s15, s15, 0
	s_add_u32 s71, s16, 0x100
	s_addc_u32 s74, s17, 0
	s_mov_b32 s75, -2
	s_add_u32 s16, s14, 0xfffc0080
	s_addc_u32 s17, s15, -1
	s_add_i32 s76, 0, 0x10000
	s_cmp_eq_u32 s75, 12
	s_cselect_b32 s19, s9, s17
	s_cselect_b32 s18, s69, s16
	s_cselect_b32 s17, s7, s74
	s_cselect_b32 s16, s70, s71
	s_add_i32 s80, 0, 0x14000
	v_add_u32_e32 v142, s76, v235
	v_add_u32_e32 v158, s80, v235
	ds_read_b128 v[130:133], v142
	ds_read_b128 v[134:137], v142 offset:1024
	ds_read_b128 v[138:141], v142 offset:2048
	ds_read_b128 v[142:145], v142 offset:3072
	ds_read_b128 v[146:149], v158
	ds_read_b128 v[150:153], v158 offset:1024
	ds_read_b128 v[154:157], v158 offset:2048
	ds_read_b128 v[158:161], v158 offset:3072
	v_lshl_add_u64 v[214:215], s[14:15], 0, v[206:207]
	s_add_i32 m0, s21, 0xc000
	ds_read_b128 v[162:165], v237
	ds_read_b128 v[166:169], v237 offset:1024
	ds_read_b128 v[170:173], v237 offset:2048
	ds_read_b128 v[174:177], v237 offset:3072
	ds_read_b128 v[178:181], v237 offset:4096
	ds_read_b128 v[182:185], v237 offset:5120
	ds_read_b128 v[186:189], v237 offset:6144
	ds_read_b128 v[210:213], v237 offset:7168
	global_load_lds_dwordx4 v[214:215], off
	v_lshl_add_u64 v[214:215], s[14:15], 0, v[208:209]
	s_add_i32 m0, s21, 0xe000
	s_nop 0
	global_load_lds_dwordx4 v[214:215], off
	s_waitcnt vmcnt(8)
	s_waitcnt lgkmcnt(0)
	s_barrier
	s_setprio 1
	s_waitcnt lgkmcnt(0)
	v_mfma_f32_16x16x32_bf16 v[126:129], v[130:133], v[162:165], 0
	v_mfma_f32_16x16x32_bf16 v[122:125], v[138:141], v[162:165], 0
	v_mfma_f32_16x16x32_bf16 v[114:117], v[130:133], v[170:173], 0
	v_mfma_f32_16x16x32_bf16 v[106:109], v[138:141], v[170:173], 0
	v_mfma_f32_16x16x32_bf16 v[98:101], v[130:133], v[178:181], 0
	v_mfma_f32_16x16x32_bf16 v[90:93], v[138:141], v[178:181], 0
	v_mfma_f32_16x16x32_bf16 v[82:85], v[130:133], v[186:189], 0
	v_mfma_f32_16x16x32_bf16 v[74:77], v[138:141], v[186:189], 0
	v_mfma_f32_16x16x32_bf16 v[126:129], v[134:137], v[166:169], v[126:129]
	v_mfma_f32_16x16x32_bf16 v[122:125], v[142:145], v[166:169], v[122:125]
	v_mfma_f32_16x16x32_bf16 v[114:117], v[134:137], v[174:177], v[114:117]
	v_mfma_f32_16x16x32_bf16 v[106:109], v[142:145], v[174:177], v[106:109]
	v_mfma_f32_16x16x32_bf16 v[98:101], v[134:137], v[182:185], v[98:101]
	v_mfma_f32_16x16x32_bf16 v[90:93], v[142:145], v[182:185], v[90:93]
	v_mfma_f32_16x16x32_bf16 v[82:85], v[134:137], v[210:213], v[82:85]
	v_mfma_f32_16x16x32_bf16 v[74:77], v[142:145], v[210:213], v[74:77]
	s_setprio 0
	s_setprio 1
	v_mfma_f32_16x16x32_bf16 v[118:121], v[146:149], v[162:165], 0
	v_mfma_f32_16x16x32_bf16 v[110:113], v[154:157], v[162:165], 0
	v_mfma_f32_16x16x32_bf16 v[102:105], v[146:149], v[170:173], 0
	v_mfma_f32_16x16x32_bf16 v[94:97], v[154:157], v[170:173], 0
	v_mfma_f32_16x16x32_bf16 v[86:89], v[146:149], v[178:181], 0
	v_mfma_f32_16x16x32_bf16 v[78:81], v[154:157], v[178:181], 0
	v_mfma_f32_16x16x32_bf16 v[70:73], v[146:149], v[186:189], 0
	v_mfma_f32_16x16x32_bf16 v[66:69], v[154:157], v[186:189], 0
	v_mfma_f32_16x16x32_bf16 v[118:121], v[150:153], v[166:169], v[118:121]
	v_mfma_f32_16x16x32_bf16 v[110:113], v[158:161], v[166:169], v[110:113]
	v_mfma_f32_16x16x32_bf16 v[102:105], v[150:153], v[174:177], v[102:105]
	v_mfma_f32_16x16x32_bf16 v[94:97], v[158:161], v[174:177], v[94:97]
	v_mfma_f32_16x16x32_bf16 v[86:89], v[150:153], v[182:185], v[86:89]
	v_mfma_f32_16x16x32_bf16 v[78:81], v[158:161], v[182:185], v[78:81]
	v_mfma_f32_16x16x32_bf16 v[70:73], v[150:153], v[210:213], v[70:73]
	v_mfma_f32_16x16x32_bf16 v[66:69], v[158:161], v[210:213], v[66:69]
	s_setprio 0
	s_barrier
	s_add_i32 s76, s76, s20
	v_lshl_add_u64 v[214:215], s[16:17], 0, v[202:203]
	s_mov_b32 m0, s76
	ds_read_b128 v[162:165], v237 offset:16384
	ds_read_b128 v[166:169], v237 offset:17408
	ds_read_b128 v[170:173], v237 offset:18432
	ds_read_b128 v[174:177], v237 offset:19456
	ds_read_b128 v[178:181], v237 offset:20480
	ds_read_b128 v[182:185], v237 offset:21504
	ds_read_b128 v[186:189], v237 offset:22528
	ds_read_b128 v[210:213], v237 offset:23552
	global_load_lds_dwordx4 v[214:215], off
	s_add_i32 m0, s76, 0x2000
	s_add_u32 s76, s16, 0x40000
	v_lshl_add_u64 v[216:217], s[16:17], 0, v[198:199]
	s_addc_u32 s77, s17, 0
	s_add_i32 s80, s80, s20
	global_load_lds_dwordx4 v[216:217], off
	v_lshl_add_u64 v[218:219], s[76:77], 0, v[202:203]
	s_mov_b32 m0, s80
	v_lshl_add_u64 v[220:221], s[18:19], 0, v[200:201]
	global_load_lds_dwordx4 v[218:219], off
	v_lshl_add_u64 v[218:219], s[76:77], 0, v[198:199]
	s_add_i32 m0, s80, 0x2000
	s_nop 0
	global_load_lds_dwordx4 v[218:219], off
	v_lshl_add_u64 v[218:219], s[18:19], 0, v[204:205]
	s_mov_b32 m0, s21
	s_nop 0
	global_load_lds_dwordx4 v[218:219], off
	s_mov_b32 m0, s25
	s_nop 0
	global_load_lds_dwordx4 v[220:221], off
	s_waitcnt vmcnt(8)
	s_waitcnt lgkmcnt(0)
	s_barrier
	s_setprio 1
	s_waitcnt lgkmcnt(0)
	v_mfma_f32_16x16x32_bf16 v[62:65], v[130:133], v[162:165], 0
	v_mfma_f32_16x16x32_bf16 v[58:61], v[138:141], v[162:165], 0
	v_mfma_f32_16x16x32_bf16 v[50:53], v[130:133], v[170:173], 0
	v_mfma_f32_16x16x32_bf16 v[42:45], v[138:141], v[170:173], 0
	v_mfma_f32_16x16x32_bf16 v[34:37], v[130:133], v[178:181], 0
	v_mfma_f32_16x16x32_bf16 v[26:29], v[138:141], v[178:181], 0
	v_mfma_f32_16x16x32_bf16 v[18:21], v[130:133], v[186:189], 0
	v_mfma_f32_16x16x32_bf16 v[10:13], v[138:141], v[186:189], 0
	v_mfma_f32_16x16x32_bf16 v[62:65], v[134:137], v[166:169], v[62:65]
	v_mfma_f32_16x16x32_bf16 v[58:61], v[142:145], v[166:169], v[58:61]
	v_mfma_f32_16x16x32_bf16 v[50:53], v[134:137], v[174:177], v[50:53]
	v_mfma_f32_16x16x32_bf16 v[42:45], v[142:145], v[174:177], v[42:45]
	v_mfma_f32_16x16x32_bf16 v[34:37], v[134:137], v[182:185], v[34:37]
	v_mfma_f32_16x16x32_bf16 v[26:29], v[142:145], v[182:185], v[26:29]
	v_mfma_f32_16x16x32_bf16 v[18:21], v[134:137], v[210:213], v[18:21]
	v_mfma_f32_16x16x32_bf16 v[10:13], v[142:145], v[210:213], v[10:13]
	s_setprio 0
	s_setprio 1
	v_mfma_f32_16x16x32_bf16 v[54:57], v[146:149], v[162:165], 0
	v_mfma_f32_16x16x32_bf16 v[46:49], v[154:157], v[162:165], 0
	v_mfma_f32_16x16x32_bf16 v[38:41], v[146:149], v[170:173], 0
	v_mfma_f32_16x16x32_bf16 v[30:33], v[154:157], v[170:173], 0
	v_mfma_f32_16x16x32_bf16 v[22:25], v[146:149], v[178:181], 0
	v_mfma_f32_16x16x32_bf16 v[14:17], v[154:157], v[178:181], 0
	v_mfma_f32_16x16x32_bf16 v[6:9], v[146:149], v[186:189], 0
	v_mfma_f32_16x16x32_bf16 v[2:5], v[154:157], v[186:189], 0
	v_mfma_f32_16x16x32_bf16 v[54:57], v[150:153], v[166:169], v[54:57]
	v_mfma_f32_16x16x32_bf16 v[46:49], v[158:161], v[166:169], v[46:49]
	v_mfma_f32_16x16x32_bf16 v[38:41], v[150:153], v[174:177], v[38:41]
	v_mfma_f32_16x16x32_bf16 v[30:33], v[158:161], v[174:177], v[30:33]
	v_mfma_f32_16x16x32_bf16 v[22:25], v[150:153], v[182:185], v[22:25]
	v_mfma_f32_16x16x32_bf16 v[14:17], v[158:161], v[182:185], v[14:17]
	v_mfma_f32_16x16x32_bf16 v[6:9], v[150:153], v[210:213], v[6:9]
	v_mfma_f32_16x16x32_bf16 v[2:5], v[158:161], v[210:213], v[2:5]
	s_setprio 0
	s_barrier
	s_add_i32 s76, 0, 0x18000
	s_add_i32 s77, 0, 0x1c000
	v_add_u32_e32 v142, s76, v235
	v_add_u32_e32 v158, s77, v235
	ds_read_b128 v[130:133], v142
	ds_read_b128 v[134:137], v142 offset:1024
	ds_read_b128 v[138:141], v142 offset:2048
	ds_read_b128 v[142:145], v142 offset:3072
	ds_read_b128 v[146:149], v158
	ds_read_b128 v[150:153], v158 offset:1024
	ds_read_b128 v[154:157], v158 offset:2048
	ds_read_b128 v[158:161], v158 offset:3072
	s_add_u32 s18, s18, 0x40000
	s_addc_u32 s19, s19, 0
	s_mov_b32 m0, s42
	v_lshl_add_u64 v[222:223], s[18:19], 0, v[204:205]
	ds_read_b128 v[162:165], v237 offset:32768
	ds_read_b128 v[166:169], v237 offset:33792
	ds_read_b128 v[170:173], v237 offset:34816
	ds_read_b128 v[174:177], v237 offset:35840
	ds_read_b128 v[178:181], v237 offset:36864
	ds_read_b128 v[182:185], v237 offset:37888
	ds_read_b128 v[186:189], v237 offset:38912
	ds_read_b128 v[210:213], v237 offset:39936
	global_load_lds_dwordx4 v[222:223], off
	v_lshl_add_u64 v[222:223], s[18:19], 0, v[200:201]
	s_mov_b32 m0, s43
	s_nop 0
	global_load_lds_dwordx4 v[222:223], off
	s_waitcnt vmcnt(8)
	s_waitcnt lgkmcnt(0)
	s_barrier
	s_setprio 1
	s_waitcnt lgkmcnt(0)
	v_mfma_f32_16x16x32_bf16 v[126:129], v[130:133], v[162:165], v[126:129]
	v_mfma_f32_16x16x32_bf16 v[122:125], v[138:141], v[162:165], v[122:125]
	v_mfma_f32_16x16x32_bf16 v[114:117], v[130:133], v[170:173], v[114:117]
	v_mfma_f32_16x16x32_bf16 v[106:109], v[138:141], v[170:173], v[106:109]
	v_mfma_f32_16x16x32_bf16 v[98:101], v[130:133], v[178:181], v[98:101]
	v_mfma_f32_16x16x32_bf16 v[90:93], v[138:141], v[178:181], v[90:93]
	v_mfma_f32_16x16x32_bf16 v[82:85], v[130:133], v[186:189], v[82:85]
	v_mfma_f32_16x16x32_bf16 v[74:77], v[138:141], v[186:189], v[74:77]
	v_mfma_f32_16x16x32_bf16 v[126:129], v[134:137], v[166:169], v[126:129]
	v_mfma_f32_16x16x32_bf16 v[122:125], v[142:145], v[166:169], v[122:125]
	v_mfma_f32_16x16x32_bf16 v[114:117], v[134:137], v[174:177], v[114:117]
	v_mfma_f32_16x16x32_bf16 v[106:109], v[142:145], v[174:177], v[106:109]
	v_mfma_f32_16x16x32_bf16 v[98:101], v[134:137], v[182:185], v[98:101]
	v_mfma_f32_16x16x32_bf16 v[90:93], v[142:145], v[182:185], v[90:93]
	v_mfma_f32_16x16x32_bf16 v[82:85], v[134:137], v[210:213], v[82:85]
	v_mfma_f32_16x16x32_bf16 v[74:77], v[142:145], v[210:213], v[74:77]
	s_setprio 0
	s_setprio 1
	v_mfma_f32_16x16x32_bf16 v[118:121], v[146:149], v[162:165], v[118:121]
	v_mfma_f32_16x16x32_bf16 v[110:113], v[154:157], v[162:165], v[110:113]
	v_mfma_f32_16x16x32_bf16 v[102:105], v[146:149], v[170:173], v[102:105]
	v_mfma_f32_16x16x32_bf16 v[94:97], v[154:157], v[170:173], v[94:97]
	v_mfma_f32_16x16x32_bf16 v[86:89], v[146:149], v[178:181], v[86:89]
	v_mfma_f32_16x16x32_bf16 v[78:81], v[154:157], v[178:181], v[78:81]
	v_mfma_f32_16x16x32_bf16 v[70:73], v[146:149], v[186:189], v[70:73]
	v_mfma_f32_16x16x32_bf16 v[66:69], v[154:157], v[186:189], v[66:69]
	v_mfma_f32_16x16x32_bf16 v[118:121], v[150:153], v[166:169], v[118:121]
	v_mfma_f32_16x16x32_bf16 v[110:113], v[158:161], v[166:169], v[110:113]
	v_mfma_f32_16x16x32_bf16 v[102:105], v[150:153], v[174:177], v[102:105]
	v_mfma_f32_16x16x32_bf16 v[94:97], v[158:161], v[174:177], v[94:97]
	v_mfma_f32_16x16x32_bf16 v[86:89], v[150:153], v[182:185], v[86:89]
	v_mfma_f32_16x16x32_bf16 v[78:81], v[158:161], v[182:185], v[78:81]
	v_mfma_f32_16x16x32_bf16 v[70:73], v[150:153], v[210:213], v[70:73]
	v_mfma_f32_16x16x32_bf16 v[66:69], v[158:161], v[210:213], v[66:69]
	s_setprio 0
	s_barrier
	s_add_i32 s18, s76, s20
	v_lshl_add_u64 v[214:215], v[214:215], 0, s[48:49]
	s_mov_b32 m0, s18
	ds_read_b128 v[162:165], v237 offset:49152
	ds_read_b128 v[166:169], v237 offset:50176
	ds_read_b128 v[170:173], v237 offset:51200
	ds_read_b128 v[174:177], v237 offset:52224
	ds_read_b128 v[178:181], v237 offset:53248
	ds_read_b128 v[182:185], v237 offset:54272
	ds_read_b128 v[186:189], v237 offset:55296
	ds_read_b128 v[210:213], v237 offset:56320
	global_load_lds_dwordx4 v[214:215], off
	s_add_i32 m0, s18, 0x2000
	s_add_u32 s16, s16, 0x40080
	v_lshl_add_u64 v[214:215], v[216:217], 0, s[48:49]
	s_addc_u32 s17, s17, 0
	s_add_i32 s18, s77, s20
	global_load_lds_dwordx4 v[214:215], off
	v_lshl_add_u64 v[214:215], s[16:17], 0, v[202:203]
	s_mov_b32 m0, s18
	s_nop 0
	global_load_lds_dwordx4 v[214:215], off
	v_lshl_add_u64 v[214:215], s[16:17], 0, v[198:199]
	s_add_i32 m0, s18, 0x2000
	s_nop 0
	global_load_lds_dwordx4 v[214:215], off
	v_lshl_add_u64 v[214:215], v[218:219], 0, s[48:49]
	s_mov_b32 m0, s44
	s_nop 0
	global_load_lds_dwordx4 v[214:215], off
	v_lshl_add_u64 v[214:215], v[220:221], 0, s[48:49]
	s_mov_b32 m0, s45
	s_nop 0
	global_load_lds_dwordx4 v[214:215], off
	s_waitcnt vmcnt(8)
	s_waitcnt lgkmcnt(0)
	s_barrier
	s_setprio 1
	s_waitcnt lgkmcnt(0)
	v_mfma_f32_16x16x32_bf16 v[62:65], v[130:133], v[162:165], v[62:65]
	v_mfma_f32_16x16x32_bf16 v[58:61], v[138:141], v[162:165], v[58:61]
	v_mfma_f32_16x16x32_bf16 v[50:53], v[130:133], v[170:173], v[50:53]
	v_mfma_f32_16x16x32_bf16 v[42:45], v[138:141], v[170:173], v[42:45]
	v_mfma_f32_16x16x32_bf16 v[34:37], v[130:133], v[178:181], v[34:37]
	v_mfma_f32_16x16x32_bf16 v[26:29], v[138:141], v[178:181], v[26:29]
	v_mfma_f32_16x16x32_bf16 v[18:21], v[130:133], v[186:189], v[18:21]
	v_mfma_f32_16x16x32_bf16 v[10:13], v[138:141], v[186:189], v[10:13]
	v_mfma_f32_16x16x32_bf16 v[62:65], v[134:137], v[166:169], v[62:65]
	v_mfma_f32_16x16x32_bf16 v[58:61], v[142:145], v[166:169], v[58:61]
	v_mfma_f32_16x16x32_bf16 v[50:53], v[134:137], v[174:177], v[50:53]
	v_mfma_f32_16x16x32_bf16 v[42:45], v[142:145], v[174:177], v[42:45]
	v_mfma_f32_16x16x32_bf16 v[34:37], v[134:137], v[182:185], v[34:37]
	v_mfma_f32_16x16x32_bf16 v[26:29], v[142:145], v[182:185], v[26:29]
	v_mfma_f32_16x16x32_bf16 v[18:21], v[134:137], v[210:213], v[18:21]
	v_mfma_f32_16x16x32_bf16 v[10:13], v[142:145], v[210:213], v[10:13]
	s_setprio 0
	s_setprio 1
	v_mfma_f32_16x16x32_bf16 v[54:57], v[146:149], v[162:165], v[54:57]
	v_mfma_f32_16x16x32_bf16 v[46:49], v[154:157], v[162:165], v[46:49]
	v_mfma_f32_16x16x32_bf16 v[38:41], v[146:149], v[170:173], v[38:41]
	v_mfma_f32_16x16x32_bf16 v[30:33], v[154:157], v[170:173], v[30:33]
	v_mfma_f32_16x16x32_bf16 v[22:25], v[146:149], v[178:181], v[22:25]
	v_mfma_f32_16x16x32_bf16 v[14:17], v[154:157], v[178:181], v[14:17]
	v_mfma_f32_16x16x32_bf16 v[6:9], v[146:149], v[186:189], v[6:9]
	v_mfma_f32_16x16x32_bf16 v[2:5], v[154:157], v[186:189], v[2:5]
	v_mfma_f32_16x16x32_bf16 v[54:57], v[150:153], v[166:169], v[54:57]
	v_mfma_f32_16x16x32_bf16 v[46:49], v[158:161], v[166:169], v[46:49]
	v_mfma_f32_16x16x32_bf16 v[38:41], v[150:153], v[174:177], v[38:41]
	v_mfma_f32_16x16x32_bf16 v[30:33], v[158:161], v[174:177], v[30:33]
	v_mfma_f32_16x16x32_bf16 v[22:25], v[150:153], v[182:185], v[22:25]
	v_mfma_f32_16x16x32_bf16 v[14:17], v[158:161], v[182:185], v[14:17]
	v_mfma_f32_16x16x32_bf16 v[6:9], v[150:153], v[210:213], v[6:9]
	v_mfma_f32_16x16x32_bf16 v[2:5], v[158:161], v[210:213], v[2:5]
	s_setprio 0
	s_barrier
	s_add_i32 s75, s75, 2
	s_add_u32 s14, s14, 0x100
	s_addc_u32 s15, s15, 0
	s_add_u32 s71, s71, 0x100
	s_addc_u32 s74, s74, 0
	s_cmp_gt_u32 s75, 13
	s_cbranch_scc0 .LBB0_1370
